# nt cache hint on the once-read x row loads of the three norm phases and on the final out stores
# speedup vs baseline: 1.0200x; 1.0186x over previous
.LBB0_101:
	v_ashrrev_i32_e32 v57, 31, v56
	v_lshlrev_b64 v[2:3], 12, v[56:57]
	v_lshl_add_u64 v[2:3], v[52:53], 0, v[2:3]
	global_load_dwordx4 v[26:29], v[2:3], off nt
	global_load_dwordx4 v[18:21], v[2:3], off offset:1024 nt
	global_load_dwordx4 v[10:13], v[2:3], off offset:2048 nt
	global_load_dwordx4 v[6:9], v[2:3], off offset:3072 nt
	v_add_u32_e32 v41, s6, v56
	v_cmp_gt_i32_e32 vcc, s7, v41
	v_mov_b32_e32 v2, 0
	v_mov_b32_e32 v3, 0
	v_cndmask_b32_e32 v58, v56, v41, vcc
	v_ashrrev_i32_e32 v59, 31, v58
	v_mov_b32_e32 v4, 0
	v_mov_b32_e32 v5, 0
	v_mov_b32_e32 v30, 0
	v_mov_b32_e32 v31, 0
	v_mov_b32_e32 v32, 0
	v_mov_b32_e32 v33, 0
	v_mov_b32_e32 v22, 0
	v_mov_b32_e32 v23, 0
	v_mov_b32_e32 v24, 0
	v_mov_b32_e32 v25, 0
	v_mov_b32_e32 v14, 0
	v_mov_b32_e32 v15, 0
	v_mov_b32_e32 v16, 0
	v_mov_b32_e32 v17, 0
	v_mov_b32_e32 v34, 0
	v_mov_b32_e32 v35, 0
	v_mov_b32_e32 v36, 0
	v_mov_b32_e32 v37, 0
	s_and_saveexec_b64 s[0:1], vcc
	s_cbranch_execz .LBB0_103
	v_lshlrev_b64 v[2:3], 12, v[58:59]
	v_lshl_add_u64 v[22:23], v[52:53], 0, v[2:3]
	global_load_dwordx4 v[2:5], v[22:23], off offset:3072 nt
	global_load_dwordx4 v[14:17], v[22:23], off offset:2048 nt
	global_load_dwordx4 v[30:33], v[22:23], off nt
	s_nop 0
	global_load_dwordx4 v[22:25], v[22:23], off offset:1024 nt
	s_waitcnt vmcnt(3)
	v_mov_b32_e32 v34, v2
	v_mov_b32_e32 v35, v3
	v_mov_b32_e32 v36, v4
	v_mov_b32_e32 v37, v5

.LBB0_1044:
	v_ashrrev_i32_e32 v53, 31, v52
	v_lshlrev_b64 v[2:3], 12, v[52:53]
	v_lshl_add_u64 v[44:45], v[38:39], 0, v[2:3]
	global_load_dwordx4 v[14:17], v[44:45], off nt
	global_load_dwordx4 v[10:13], v[44:45], off offset:1024 nt
	global_load_dwordx4 v[2:5], v[44:45], off offset:2048 nt
	global_load_dwordx4 v[6:9], v[44:45], off offset:3072 nt
	v_lshlrev_b64 v[44:45], 11, v[52:53]
	v_lshl_add_u64 v[44:45], v[40:41], 0, v[44:45]
	global_load_dwordx2 v[72:73], v[44:45], off
	global_load_dwordx2 v[74:75], v[44:45], off offset:512
	global_load_dwordx2 v[68:69], v[44:45], off offset:1024
	global_load_dwordx2 v[70:71], v[44:45], off offset:1536
	v_add_u32_e32 v21, s4, v52
	v_cmp_gt_i32_e32 vcc, s5, v21
	v_mov_b32_e32 v60, 0
	v_mov_b32_e32 v61, 0
	v_cndmask_b32_e32 v64, v52, v21, vcc
	v_ashrrev_i32_e32 v65, 31, v64
	v_lshlrev_b64 v[56:57], 11, v[64:65]
	v_mov_b32_e32 v62, 0
	v_mov_b32_e32 v63, 0
	v_mov_b32_e32 v54, 0
	v_mov_b32_e32 v55, 0
	v_mov_b32_e32 v58, 0
	v_mov_b32_e32 v59, 0
	v_mov_b32_e32 v48, 0
	v_mov_b32_e32 v49, 0
	v_mov_b32_e32 v50, 0
	v_mov_b32_e32 v51, 0
	v_mov_b32_e32 v44, 0
	v_mov_b32_e32 v45, 0
	v_mov_b32_e32 v46, 0
	v_mov_b32_e32 v47, 0
	s_and_saveexec_b64 s[0:1], vcc
	s_cbranch_execz .LBB0_1046
	v_lshl_add_u64 v[44:45], v[40:41], 0, v[56:57]
	global_load_dwordx2 v[54:55], v[44:45], off
	global_load_dwordx2 v[58:59], v[44:45], off offset:512
	global_load_dwordx2 v[60:61], v[44:45], off offset:1024
	global_load_dwordx2 v[62:63], v[44:45], off offset:1536
	v_lshlrev_b64 v[44:45], 12, v[64:65]
	v_lshl_add_u64 v[82:83], v[38:39], 0, v[44:45]
	global_load_dwordx4 v[44:47], v[82:83], off nt
	global_load_dwordx4 v[48:51], v[82:83], off offset:1024 nt
	global_load_dwordx4 v[64:67], v[82:83], off offset:2048 nt
	global_load_dwordx4 v[78:81], v[82:83], off offset:3072 nt
	s_waitcnt vmcnt(0)
	v_lshlrev_b32_e32 v82, 16, v54
	v_and_b32_e32 v83, 0xffff0000, v54
	v_lshlrev_b32_e32 v54, 16, v55
	v_and_b32_e32 v55, 0xffff0000, v55
	v_lshlrev_b32_e32 v84, 16, v58
	v_and_b32_e32 v85, 0xffff0000, v58
	v_lshlrev_b32_e32 v58, 16, v59
	v_and_b32_e32 v59, 0xffff0000, v59
	v_lshlrev_b32_e32 v86, 16, v60
	v_and_b32_e32 v87, 0xffff0000, v60
	v_lshlrev_b32_e32 v88, 16, v61
	v_and_b32_e32 v89, 0xffff0000, v61
	v_lshlrev_b32_e32 v90, 16, v62
	v_and_b32_e32 v91, 0xffff0000, v62
	v_lshlrev_b32_e32 v92, 16, v63
	v_and_b32_e32 v93, 0xffff0000, v63
	v_pk_add_f32 v[60:61], v[44:45], v[82:83]
	v_pk_add_f32 v[62:63], v[46:47], v[54:55]
	v_pk_add_f32 v[54:55], v[48:49], v[84:85]
	v_pk_add_f32 v[58:59], v[50:51], v[58:59]
	v_pk_add_f32 v[48:49], v[64:65], v[86:87]
	v_pk_add_f32 v[50:51], v[66:67], v[88:89]
	v_pk_add_f32 v[44:45], v[78:79], v[90:91]
	v_pk_add_f32 v[46:47], v[80:81], v[92:93]

.LBB0_1454:
	s_or_b64 exec, exec, s[0:1]
	v_mov_b32_e32 v39, v30
	v_add_u32_e32 v52, s6, v52
	s_add_u32 s16, s16, s10
	v_pk_mul_f32 v[2:3], v[38:39], v[18:19]
	v_pk_mul_f32 v[4:5], v[30:31], v[20:21] op_sel_hi:[0,1]
	s_addc_u32 s17, s17, s11
	v_cmp_lt_i32_e32 vcc, s7, v52
	s_waitcnt vmcnt(0)
	v_pk_mul_f32 v[4:5], v[4:5], v[24:25]
	v_pk_mul_f32 v[2:3], v[2:3], v[22:23]
	v_lshl_add_u64 v[6:7], v[98:99], 0, v[56:57]
	v_lshl_add_u64 v[66:67], v[66:67], 0, s[8:9]
	v_lshl_add_u64 v[74:75], v[74:75], 0, s[10:11]
	s_or_b64 s[12:13], vcc, s[12:13]
	v_lshl_add_u64 v[70:71], v[70:71], 0, s[10:11]
	global_store_dwordx4 v[6:7], v[2:5], off offset:3072 nt
	s_andn2_b64 exec, exec, s[12:13]
	s_cbranch_execz .LBB0_1465
.LBB0_1455:
	v_lshl_add_u64 v[2:3], v[74:75], 0, v[68:69]
	global_load_dwordx4 v[26:29], v[2:3], off nt
	global_load_dwordx4 v[22:25], v[2:3], off offset:1024 nt
	global_load_dwordx4 v[10:13], v[2:3], off offset:2048 nt
	global_load_dwordx4 v[18:21], v[2:3], off offset:3072 nt
	global_load_dwordx2 v[44:45], v[66:67], off
	global_load_dwordx2 v[46:47], v[66:67], off offset:512
	global_load_dwordx2 v[34:35], v[66:67], off offset:1024
	global_load_dwordx2 v[36:37], v[66:67], off offset:1536
	v_add_co_u32_e32 v2, vcc, 0xef000000, v66
	v_mov_b32_e32 v84, 0
	s_nop 0
	v_addc_co_u32_e32 v3, vcc, -1, v67, vcc
	v_add_co_u32_e32 v4, vcc, 0xef001000, v66
	v_mov_b32_e32 v85, 0
	s_nop 0
	v_addc_co_u32_e32 v5, vcc, -1, v67, vcc
	global_load_dwordx2 v[38:39], v[2:3], off
	global_load_dwordx2 v[42:43], v[4:5], off offset:-3584
	global_load_dwordx2 v[30:31], v[4:5], off offset:-3072
	global_load_dwordx2 v[32:33], v[4:5], off offset:-2560
	v_add_u32_e32 v2, s22, v52
	v_cmp_gt_i32_e64 s[0:1], s15, v2
	v_cmp_lt_i32_e32 vcc, s7, v2
	v_mov_b32_e32 v3, 0
	v_cndmask_b32_e64 v48, v52, v2, s[0:1]
	v_ashrrev_i32_e32 v49, 31, v48
	v_lshlrev_b64 v[4:5], 12, v[48:49]
	v_mov_b32_e32 v2, 0
	v_mov_b32_e32 v6, 0
	v_mov_b32_e32 v7, 0
	v_mov_b32_e32 v8, 0
	v_mov_b32_e32 v9, 0
	v_mov_b32_e32 v40, 0
	v_mov_b32_e32 v41, 0
	v_mov_b32_e32 v76, 0
	v_mov_b32_e32 v77, 0
	v_mov_b32_e32 v14, 0
	v_mov_b32_e32 v15, 0
	v_mov_b32_e32 v16, 0
	v_mov_b32_e32 v17, 0
	s_and_saveexec_b64 s[2:3], s[0:1]
	s_cbranch_execz .LBB0_1457
	v_lshlrev_b64 v[2:3], 11, v[48:49]
	v_lshl_add_u64 v[6:7], v[62:63], 0, v[2:3]
	v_lshl_add_u64 v[2:3], v[64:65], 0, v[2:3]
	global_load_dwordx2 v[40:41], v[6:7], off
	global_load_dwordx2 v[80:81], v[2:3], off
	global_load_dwordx2 v[82:83], v[6:7], off offset:512
	global_load_dwordx2 v[84:85], v[2:3], off offset:512
	global_load_dwordx2 v[86:87], v[6:7], off offset:1024
	global_load_dwordx2 v[88:89], v[2:3], off offset:1024
	global_load_dwordx2 v[90:91], v[6:7], off offset:1536
	global_load_dwordx2 v[92:93], v[2:3], off offset:1536
	v_lshl_add_u64 v[2:3], v[60:61], 0, v[4:5]
	global_load_dwordx4 v[6:9], v[2:3], off nt
	global_load_dwordx4 v[14:17], v[2:3], off offset:1024 nt
	global_load_dwordx4 v[48:51], v[2:3], off offset:2048 nt
	global_load_dwordx4 v[76:79], v[2:3], off offset:3072 nt
	s_waitcnt vmcnt(10)
	v_lshlrev_b32_e32 v94, 16, v80
	s_waitcnt vmcnt(9)
	v_lshlrev_b32_e32 v96, 16, v82
	v_and_b32_e32 v97, 0xffff0000, v82
	s_waitcnt vmcnt(8)
	v_lshlrev_b32_e32 v98, 16, v84
	v_and_b32_e32 v99, 0xffff0000, v84
	v_lshlrev_b32_e32 v2, 16, v40
	v_and_b32_e32 v3, 0xffff0000, v40
	v_lshlrev_b32_e32 v40, 16, v41
	v_and_b32_e32 v41, 0xffff0000, v41
	v_lshlrev_b32_e32 v82, 16, v83
	v_and_b32_e32 v83, 0xffff0000, v83
	v_lshlrev_b32_e32 v100, 16, v85
	v_and_b32_e32 v101, 0xffff0000, v85
	s_waitcnt vmcnt(7)
	v_lshlrev_b32_e32 v84, 16, v86
	v_and_b32_e32 v85, 0xffff0000, v86
	v_lshlrev_b32_e32 v86, 16, v87
	v_and_b32_e32 v87, 0xffff0000, v87
	s_waitcnt vmcnt(5)
	v_lshlrev_b32_e32 v108, 16, v90
	v_and_b32_e32 v109, 0xffff0000, v90
	v_lshlrev_b32_e32 v90, 16, v91
	v_and_b32_e32 v91, 0xffff0000, v91
	v_and_b32_e32 v95, 0xffff0000, v80
	v_lshlrev_b32_e32 v80, 16, v81
	v_and_b32_e32 v81, 0xffff0000, v81
	v_lshlrev_b32_e32 v106, 16, v88
	v_and_b32_e32 v107, 0xffff0000, v88
	v_lshlrev_b32_e32 v88, 16, v89
	v_and_b32_e32 v89, 0xffff0000, v89
	s_waitcnt vmcnt(4)
	v_lshlrev_b32_e32 v110, 16, v92
	v_and_b32_e32 v111, 0xffff0000, v92
	v_lshlrev_b32_e32 v92, 16, v93
	v_and_b32_e32 v93, 0xffff0000, v93
	s_waitcnt vmcnt(3)
	v_pk_add_f32 v[2:3], v[6:7], v[2:3]
	v_pk_add_f32 v[6:7], v[8:9], v[40:41]
	s_waitcnt vmcnt(2)
	v_pk_add_f32 v[8:9], v[14:15], v[96:97]
	v_pk_add_f32 v[14:15], v[16:17], v[82:83]
	s_waitcnt vmcnt(1)
	v_pk_add_f32 v[16:17], v[48:49], v[84:85]
	v_pk_add_f32 v[48:49], v[50:51], v[86:87]
	s_waitcnt vmcnt(0)
	v_pk_add_f32 v[50:51], v[76:77], v[108:109]
	v_pk_add_f32 v[78:79], v[78:79], v[90:91]
	v_pk_add_f32 v[2:3], v[2:3], v[94:95]
	v_pk_add_f32 v[84:85], v[6:7], v[80:81]
	v_pk_add_f32 v[6:7], v[8:9], v[98:99]
	v_pk_add_f32 v[8:9], v[14:15], v[100:101]
	v_pk_add_f32 v[40:41], v[16:17], v[106:107]
	v_pk_add_f32 v[76:77], v[48:49], v[88:89]
	v_pk_add_f32 v[14:15], v[50:51], v[110:111]
	v_pk_add_f32 v[16:17], v[78:79], v[92:93]
.LBB0_1457:
	s_or_b64 exec, exec, s[2:3]
	s_waitcnt vmcnt(6)
	v_lshlrev_b32_e32 v49, 16, v46
	v_lshlrev_b32_e32 v48, 16, v44
	v_mov_b32_e32 v50, v26
	v_mov_b32_e32 v51, v22
	v_pk_add_f32 v[48:49], v[50:51], v[48:49]
	v_and_b32_e32 v51, 0xffff0000, v46
	v_and_b32_e32 v50, 0xffff0000, v44
	v_mov_b32_e32 v22, v27
	v_pk_add_f32 v[22:23], v[22:23], v[50:51]
	v_lshlrev_b32_e32 v27, 16, v47
	v_mov_b32_e32 v51, v24
	v_and_b32_e32 v47, 0xffff0000, v47
	v_and_b32_e32 v46, 0xffff0000, v45
	v_mov_b32_e32 v24, v29
	v_lshlrev_b32_e32 v26, 16, v45
	v_pk_add_f32 v[24:25], v[24:25], v[46:47]
	global_load_dwordx4 v[44:47], v[58:59], off
	v_mov_b32_e32 v50, v28
	s_waitcnt vmcnt(3)
	v_lshlrev_b32_e32 v29, 16, v42
	v_lshlrev_b32_e32 v28, 16, v38
	v_pk_add_f32 v[92:93], v[48:49], v[28:29]
	v_and_b32_e32 v29, 0xffff0000, v42
	v_and_b32_e32 v28, 0xffff0000, v38
	v_pk_add_f32 v[26:27], v[50:51], v[26:27]
	v_pk_add_f32 v[88:89], v[22:23], v[28:29]
	v_lshlrev_b32_e32 v23, 16, v43
	v_lshlrev_b32_e32 v22, 16, v39
	v_pk_add_f32 v[94:95], v[26:27], v[22:23]
	v_and_b32_e32 v23, 0xffff0000, v43
	v_and_b32_e32 v22, 0xffff0000, v39
	v_pk_add_f32 v[90:91], v[24:25], v[22:23]
	v_lshlrev_b32_e32 v23, 16, v34
	v_lshlrev_b32_e32 v22, 16, v36
	v_mov_b32_e32 v24, v18
	v_mov_b32_e32 v25, v10
	v_pk_add_f32 v[22:23], v[24:25], v[22:23]
	v_and_b32_e32 v25, 0xffff0000, v34
	v_and_b32_e32 v24, 0xffff0000, v36
	v_mov_b32_e32 v10, v19
	v_pk_add_f32 v[10:11], v[10:11], v[24:25]
	v_mov_b32_e32 v24, v20
	v_mov_b32_e32 v25, v12
	v_mov_b32_e32 v12, v21
	s_waitcnt vmcnt(2)
	v_lshlrev_b32_e32 v21, 16, v30
	s_waitcnt vmcnt(1)
	v_lshlrev_b32_e32 v20, 16, v32
	v_lshlrev_b32_e32 v19, 16, v35
	v_lshlrev_b32_e32 v18, 16, v37
	v_pk_add_f32 v[78:79], v[22:23], v[20:21]
	v_and_b32_e32 v21, 0xffff0000, v30
	v_and_b32_e32 v20, 0xffff0000, v32
	v_pk_add_f32 v[18:19], v[24:25], v[18:19]
	v_pk_add_f32 v[82:83], v[10:11], v[20:21]
	v_lshlrev_b32_e32 v11, 16, v31
	v_lshlrev_b32_e32 v10, 16, v33
	v_pk_add_f32 v[80:81], v[18:19], v[10:11]
	v_and_b32_e32 v11, 0xffff0000, v31
	v_and_b32_e32 v10, 0xffff0000, v33
	v_pk_mul_f32 v[30:31], v[2:3], v[2:3]
	v_pk_mul_f32 v[32:33], v[6:7], v[6:7]
	v_and_b32_e32 v25, 0xffff0000, v35
	v_and_b32_e32 v24, 0xffff0000, v37
	v_pk_mul_f32 v[26:27], v[84:85], v[84:85]
	v_pk_mul_f32 v[28:29], v[8:9], v[8:9]
	v_mov_b32_e32 v34, v30
	v_mov_b32_e32 v35, v32
	v_mov_b32_e32 v32, v31
	v_pk_add_f32 v[12:13], v[12:13], v[24:25]
	v_pk_add_f32 v[30:31], v[34:35], v[32:33]
	v_mov_b32_e32 v32, v26
	v_mov_b32_e32 v33, v28
	v_pk_add_f32 v[86:87], v[12:13], v[10:11]
	v_pk_mul_f32 v[10:11], v[88:89], v[88:89]
	v_pk_mul_f32 v[22:23], v[14:15], v[14:15]
	v_pk_mul_f32 v[24:25], v[40:41], v[40:41]
	v_pk_add_f32 v[30:31], v[32:33], v[30:31]
	v_mov_b32_e32 v28, v27
	v_pk_fma_f32 v[10:11], v[92:93], v[92:93], v[10:11]
	v_pk_mul_f32 v[12:13], v[82:83], v[82:83]
	v_pk_mul_f32 v[18:19], v[16:17], v[16:17]
	v_pk_mul_f32 v[20:21], v[76:77], v[76:77]
	v_pk_add_f32 v[26:27], v[28:29], v[30:31]
	v_mov_b32_e32 v28, v22
	v_mov_b32_e32 v29, v24
	v_mov_b32_e32 v24, v23
	v_pk_fma_f32 v[10:11], v[94:95], v[94:95], v[10:11]
	v_pk_fma_f32 v[12:13], v[78:79], v[78:79], v[12:13]
	v_pk_add_f32 v[22:23], v[28:29], v[24:25]
	v_mov_b32_e32 v24, v18
	v_mov_b32_e32 v25, v20
	v_pk_fma_f32 v[10:11], v[90:91], v[90:91], v[10:11]
	v_pk_fma_f32 v[12:13], v[80:81], v[80:81], v[12:13]
	v_pk_add_f32 v[22:23], v[24:25], v[22:23]
	v_mov_b32_e32 v20, v19
	v_pk_fma_f32 v[12:13], v[86:87], v[86:87], v[12:13]
	v_pk_add_f32 v[18:19], v[20:21], v[22:23]
	v_mov_b32_e32 v20, v26
	v_mov_b32_e32 v21, v10
	v_mov_b32_e32 v10, v27
	v_pk_add_f32 v[10:11], v[20:21], v[10:11]
	v_mov_b32_e32 v20, v19
	v_mov_b32_e32 v21, v13
	v_pk_add_f32 v[10:11], v[20:21], v[10:11]
	v_mov_b32_e32 v19, v12
	v_pk_add_f32 v[10:11], v[18:19], v[10:11]
	ds_bpermute_b32 v13, v1, v11
	ds_bpermute_b32 v12, v1, v10
	v_mov_b32_e32 v24, v94
	v_mov_b32_e32 v25, v90
	v_lshl_add_u64 v[96:97], v[70:71], 0, v[68:69]
	s_waitcnt lgkmcnt(0)
	v_pk_add_f32 v[10:11], v[10:11], v[12:13]
	ds_bpermute_b32 v13, v55, v11
	ds_bpermute_b32 v12, v55, v10
	s_waitcnt lgkmcnt(0)
	v_pk_add_f32 v[10:11], v[10:11], v[12:13]
	ds_bpermute_b32 v13, v73, v11
	ds_bpermute_b32 v12, v73, v10
	s_waitcnt lgkmcnt(0)
	v_pk_add_f32 v[10:11], v[10:11], v[12:13]
	ds_bpermute_b32 v13, v102, v11
	ds_bpermute_b32 v12, v102, v10
	s_waitcnt lgkmcnt(0)
	v_pk_add_f32 v[12:13], v[10:11], v[12:13]
	ds_bpermute_b32 v19, v103, v13
	ds_bpermute_b32 v18, v103, v12
	v_mov_b32_e32 v10, v93
	v_mov_b32_e32 v11, v89
	s_waitcnt lgkmcnt(0)
	v_pk_add_f32 v[20:21], v[12:13], v[18:19]
	ds_bpermute_b32 v23, v104, v21
	ds_bpermute_b32 v22, v104, v20
	v_mov_b32_e32 v12, v95
	v_mov_b32_e32 v13, v91
	v_mov_b32_e32 v18, v78
	v_mov_b32_e32 v19, v82
	s_waitcnt lgkmcnt(0)
	v_pk_add_f32 v[20:21], v[20:21], v[22:23]
	s_nop 0
	v_pk_fma_f32 v[42:43], v[20:21], s[14:15], v[72:73] op_sel_hi:[1,0,0]
	v_mov_b32_e32 v21, v86
	v_mul_f32_e32 v20, 0x4b800000, v43
	v_cmp_gt_f32_e64 s[2:3], s20, v43
	v_cmp_gt_f32_e64 s[0:1], s20, v42
	s_nop 0
	v_cndmask_b32_e64 v20, v43, v20, s[2:3]
	v_rsq_f32_e32 v22, v20
	v_mov_b32_e32 v20, v80
	v_mul_f32_e32 v23, 0x45800000, v22
	v_cndmask_b32_e64 v38, v22, v23, s[2:3]
	v_mov_b32_e32 v22, v92
	v_mov_b32_e32 v23, v88
	v_pk_mul_f32 v[22:23], v[22:23], v[38:39] op_sel_hi:[1,0]
	v_pk_mul_f32 v[24:25], v[24:25], v[38:39] op_sel_hi:[1,0]
	s_waitcnt vmcnt(0)
	v_pk_mul_f32 v[22:23], v[44:45], v[22:23]
	v_pk_mul_f32 v[24:25], v[46:47], v[24:25]
	global_store_dwordx4 v[96:97], v[22:25], off nt
	s_and_saveexec_b64 s[2:3], vcc
	s_xor_b64 s[2:3], exec, s[2:3]
	s_cbranch_execz .LBB0_1459
	global_load_dwordx4 v[48:51], v[58:59], off offset:1024
	v_mov_b64_e32 v[36:37], v[20:21]
	v_mov_b64_e32 v[34:35], v[18:19]
	v_mov_b64_e32 v[32:33], v[16:17]
	v_mov_b64_e32 v[30:31], v[14:15]
	v_mov_b64_e32 v[28:29], v[12:13]
	v_mov_b64_e32 v[26:27], v[10:11]
	v_mov_b64_e32 v[24:25], v[8:9]
	v_mov_b64_e32 v[22:23], v[6:7]
.LBB0_1459:
	s_or_saveexec_b64 s[2:3], s[2:3]
	v_mul_f32_e32 v10, 0x4b800000, v42
	v_cndmask_b32_e64 v10, v42, v10, s[0:1]
	v_rsq_f32_e32 v10, v10
	v_mov_b32_e32 v39, v38
	v_lshl_add_u64 v[100:101], s[18:19], 0, v[4:5]
	v_lshl_add_u64 v[98:99], s[16:17], 0, v[68:69]
	v_mul_f32_e32 v4, 0x45800000, v10
	v_cndmask_b32_e64 v42, v10, v4, s[0:1]
	v_mov_b64_e32 v[10:11], v[38:39]
	v_mov_b32_e32 v43, v42
	v_lshlrev_b32_e32 v56, 4, v54
	v_mov_b64_e32 v[4:5], v[98:99]
	v_mov_b32_e32 v11, v38
	v_mov_b64_e32 v[12:13], v[40:41]
	s_xor_b64 exec, exec, s[2:3]
	s_cbranch_execz .LBB0_1461
	v_mov_b32_e32 v4, v42
	v_mov_b32_e32 v5, v42
	v_pk_mul_f32 v[4:5], v[84:85], v[4:5]
	v_pk_mul_f32 v[10:11], v[2:3], v[42:43]
	v_pk_mul_f32 v[12:13], v[46:47], v[4:5]
	v_pk_mul_f32 v[10:11], v[44:45], v[10:11]
	v_lshl_add_u64 v[4:5], v[100:101], 0, v[56:57]
	global_store_dwordx4 v[4:5], v[10:13], off nt
	global_load_dwordx4 v[48:51], v[58:59], off offset:1024
	v_mov_b64_e32 v[36:37], v[16:17]
	v_mov_b32_e32 v44, v38
	v_mov_b32_e32 v45, v38
	v_mov_b64_e32 v[34:35], v[14:15]
	v_mov_b64_e32 v[32:33], v[12:13]
	v_mov_b64_e32 v[30:31], v[10:11]
	v_mov_b64_e32 v[28:29], v[8:9]
	v_mov_b64_e32 v[26:27], v[6:7]
	v_mov_b64_e32 v[24:25], v[4:5]
	v_mov_b64_e32 v[22:23], v[2:3]
	v_mov_b64_e32 v[10:11], v[42:43]
	v_mov_b32_e32 v90, v95
	v_mov_b32_e32 v88, v93
	v_mov_b64_e32 v[12:13], v[44:45]
	v_pk_mul_f32 v[12:13], v[90:91], v[44:45]
	v_pk_mul_f32 v[22:23], v[88:89], v[38:39]
	v_mov_b64_e32 v[4:5], v[100:101]
	v_mov_b32_e32 v11, v42
	s_waitcnt vmcnt(0)
	v_pk_mul_f32 v[24:25], v[12:13], v[50:51]
	v_pk_mul_f32 v[22:23], v[22:23], v[48:49]
	global_store_dwordx4 v[96:97], v[22:25], off offset:1024 nt
.LBB0_1461:
	s_or_b64 exec, exec, s[2:3]
	s_nop 0
	v_pk_mul_f32 v[22:23], v[10:11], v[26:27]
	v_mov_b32_e32 v10, v11
	v_pk_mul_f32 v[10:11], v[10:11], v[28:29] op_sel_hi:[0,1]
	s_waitcnt vmcnt(0)
	v_pk_mul_f32 v[12:13], v[10:11], v[50:51]
	v_pk_mul_f32 v[10:11], v[22:23], v[48:49]
	v_lshl_add_u64 v[4:5], v[4:5], 0, v[56:57]
	global_store_dwordx4 v[4:5], v[10:13], off offset:1024 nt
	global_load_dwordx4 v[26:29], v[58:59], off offset:2048
	v_mov_b32_e32 v4, v38
	v_mov_b32_e32 v5, v38
	v_mov_b32_e32 v10, v81
	v_mov_b32_e32 v11, v87
	v_mov_b32_e32 v12, v79
	v_mov_b32_e32 v13, v83
	v_pk_mul_f32 v[4:5], v[10:11], v[4:5]
	v_pk_mul_f32 v[10:11], v[12:13], v[38:39]
	s_waitcnt vmcnt(0)
	v_pk_mul_f32 v[12:13], v[4:5], v[28:29]
	v_pk_mul_f32 v[10:11], v[10:11], v[26:27]
	global_store_dwordx4 v[96:97], v[10:13], off offset:2048 nt
	s_and_saveexec_b64 s[0:1], vcc
	s_xor_b64 s[0:1], exec, s[0:1]
	s_cbranch_execz .LBB0_1463
	global_load_dwordx4 v[22:25], v[58:59], off offset:3072
.LBB0_1463:
	s_or_saveexec_b64 s[0:1], s[0:1]
	v_mov_b32_e32 v30, v38
	s_xor_b64 exec, exec, s[0:1]
	s_cbranch_execz .LBB0_1454
	v_mov_b32_e32 v18, v42
	v_mov_b32_e32 v19, v42
	v_pk_mul_f32 v[18:19], v[76:77], v[18:19]
	s_waitcnt vmcnt(0)
	v_pk_mul_f32 v[22:23], v[40:41], v[42:43]
	v_pk_mul_f32 v[20:21], v[18:19], v[28:29]
	v_pk_mul_f32 v[18:19], v[22:23], v[26:27]
	v_lshl_add_u64 v[22:23], v[100:101], 0, v[56:57]
	global_store_dwordx4 v[22:23], v[18:21], off offset:2048 nt
	global_load_dwordx4 v[22:25], v[58:59], off offset:3072
	v_mov_b32_e32 v26, v38
	v_mov_b64_e32 v[20:21], v[16:17]
	v_mov_b32_e32 v27, v38
	v_mov_b32_e32 v81, v86
	v_mov_b32_e32 v79, v82
	v_mov_b64_e32 v[18:19], v[14:15]
	v_mov_b64_e32 v[16:17], v[12:13]
	v_mov_b64_e32 v[14:15], v[10:11]
	v_mov_b64_e32 v[12:13], v[8:9]
	v_mov_b64_e32 v[10:11], v[6:7]
	v_mov_b64_e32 v[8:9], v[4:5]
	v_mov_b64_e32 v[6:7], v[2:3]
	v_pk_mul_f32 v[2:3], v[80:81], v[26:27]
	v_pk_mul_f32 v[6:7], v[78:79], v[38:39]
	v_mov_b64_e32 v[98:99], v[100:101]
	v_mov_b64_e32 v[38:39], v[42:43]
	v_mov_b32_e32 v30, v42
	v_mov_b64_e32 v[40:41], v[44:45]
	s_waitcnt vmcnt(0)
	v_pk_mul_f32 v[4:5], v[2:3], v[24:25]
	v_pk_mul_f32 v[2:3], v[6:7], v[22:23]
	global_store_dwordx4 v[96:97], v[2:5], off offset:3072 nt
	s_branch .LBB0_1454
